# rotary epilogue: cos/sin tables of steps 5-8 fetched once per row-half by LDS-DMA into free LDS and shared by the four waves; all table data requested at epilogue start
# speedup vs baseline: 1.0002x; 1.0002x over previous
.LBB0_198:
	s_andn2_b64 vcc, exec, s[4:5]
	s_cbranch_vccnz .LBB0_200
	v_lshlrev_b32_e32 v163, 7, v162
	v_lshl_or_b32 v138, v161, 5, v163
	v_and_b32_e32 v249, 15, v162
	v_and_b32_e32 v248, 0xfffffff0, v162
	v_lshlrev_b32_e32 v248, 7, v248
	v_lshl_or_b32 v248, v249, 4, v248
	v_lshl_or_b32 v248, v161, 8, v248
	s_add_u32 s98, s82, 0xc00000
	s_addc_u32 s99, s83, 0
	s_add_u32 s100, s82, 0xe00000
	s_addc_u32 s101, s83, 0
	global_load_dwordx4 v[184:187], v248, s[98:99]
	global_load_dwordx4 v[188:191], v248, s[100:101]
	global_load_dwordx4 v[192:195], v248, s[98:99] offset:1024
	global_load_dwordx4 v[196:199], v248, s[100:101] offset:1024
	v_add_u32_e32 v249, 0x800, v248
	global_load_dwordx4 v[200:203], v249, s[98:99]
	global_load_dwordx4 v[204:207], v249, s[100:101]
	global_load_dwordx4 v[208:211], v249, s[98:99] offset:1024
	global_load_dwordx4 v[212:215], v249, s[100:101] offset:1024
	v_add_u32_e32 v250, 0x1000, v248
	global_load_dwordx4 v[216:219], v250, s[98:99]
	global_load_dwordx4 v[220:223], v250, s[100:101]
	global_load_dwordx4 v[224:227], v250, s[98:99] offset:1024
	global_load_dwordx4 v[228:231], v250, s[100:101] offset:1024
	v_add_u32_e32 v251, 0x1800, v248
	global_load_dwordx4 v[232:235], v251, s[98:99]
	global_load_dwordx4 v[236:239], v251, s[100:101]
	global_load_dwordx4 v[240:243], v251, s[98:99] offset:1024
	global_load_dwordx4 v[244:247], v251, s[100:101] offset:1024
	v_readfirstlane_b32 s84, v0
	s_lshr_b32 s84, s84, 6
	s_and_b32 s85, s84, 3
	s_lshr_b32 s84, s84, 2
	s_lshl_b32 s86, s85, 11
	s_add_i32 s86, s86, 0x4000
	v_add_u32_e32 v252, s86, v248
	v_add_u32_e32 v249, 0x400, v252
	s_cmp_eq_u32 s84, 0
	s_mov_b32 s87, 0xc000
	s_cselect_b32 s87, 0x20000, s87
	s_lshl_b32 s85, s85, 12
	s_add_i32 s85, s87, s85
	v_and_b32_e32 v253, 63, v0
	v_lshlrev_b32_e32 v253, 4, v253
	v_add_u32_e32 v253, s87, v253
	s_mov_b32 m0, s85
	s_nop 0
	global_load_lds_dwordx4 v252, s[98:99]
	s_add_i32 m0, s85, 0x400
	s_nop 0
	global_load_lds_dwordx4 v252, s[100:101]
	s_add_i32 m0, s85, 0x800
	s_nop 0
	global_load_lds_dwordx4 v249, s[98:99]
	s_add_i32 m0, s85, 0xc00
	s_nop 0
	global_load_lds_dwordx4 v249, s[100:101]
	v_lshl_add_u64 v[148:149], s[82:83], 0, v[138:139]
	v_add_co_u32_e32 v150, vcc, s51, v148
	s_cmp_lt_u32 s18, 10
	s_nop 0
	v_addc_co_u32_e32 v151, vcc, 0, v149, vcc
	v_add_co_u32_e32 v152, vcc, s50, v148
	s_nop 0
	v_addc_co_u32_e32 v153, vcc, 0, v149, vcc
	s_cselect_b64 vcc, -1, 0
	v_cndmask_b32_e32 v138, 1.0, v160, vcc
	v_add_co_u32_e64 v154, s[4:5], s48, v148
	v_mov_b32_e32 v181, v139
	s_nop 0
	v_addc_co_u32_e64 v155, s[4:5], 0, v149, s[4:5]
	v_add_co_u32_e64 v178, s[4:5], s49, v148
	s_waitcnt vmcnt(16)
	v_pk_mul_f32 v[166:167], v[138:139], v[186:187] op_sel_hi:[0,1]
	v_pk_mul_f32 v[164:165], v[138:139], v[184:185] op_sel_hi:[0,1]
	v_addc_co_u32_e64 v179, s[4:5], 0, v149, s[4:5]
	v_pk_mul_f32 v[170:171], v[138:139], v[190:191] op_sel_hi:[0,1]
	v_pk_mul_f32 v[168:169], v[138:139], v[188:189] op_sel_hi:[0,1]
	v_pk_mul_f32 v[172:173], v[120:121], v[170:171]
	v_pk_mul_f32 v[174:175], v[118:119], v[168:169]
	v_pk_mul_f32 v[168:169], v[126:127], v[168:169]
	v_pk_mul_f32 v[170:171], v[128:129], v[170:171]
	v_pk_fma_f32 v[172:173], v[128:129], v[166:167], v[172:173] neg_lo:[0,0,1] neg_hi:[0,0,1]
	v_pk_fma_f32 v[174:175], v[126:127], v[164:165], v[174:175] neg_lo:[0,0,1] neg_hi:[0,0,1]
	v_pk_fma_f32 v[168:169], v[118:119], v[164:165], v[168:169]
	v_pk_fma_f32 v[166:167], v[120:121], v[166:167], v[170:171]
	v_cvt_pk_bf16_f32 v164, v174, v175
	v_cvt_pk_bf16_f32 v165, v172, v173
	v_cvt_pk_bf16_f32 v168, v168, v169
	s_and_b64 s[4:5], vcc, exec
	v_cvt_pk_bf16_f32 v169, v166, v167
	s_cselect_b32 s4, s47, 0x6000000
	s_lshl_b32 s5, s18, 2
	s_and_b32 s5, s5, 4
	v_lshl_or_b32 v166, v161, 4, s4
	s_or_b32 s4, s11, s5
	v_lshl_or_b32 v166, s4, 21, v166
	v_add_u32_e32 v180, v166, v163
	v_pk_mul_f32 v[166:167], v[138:139], v[194:195] op_sel_hi:[0,1]
	v_pk_mul_f32 v[172:173], v[138:139], v[198:199] op_sel_hi:[0,1]
	v_pk_mul_f32 v[174:175], v[138:139], v[196:197] op_sel_hi:[0,1]
	v_pk_mul_f32 v[170:171], v[138:139], v[192:193] op_sel_hi:[0,1]
	v_pk_mul_f32 v[176:177], v[116:117], v[172:173]
	v_pk_mul_f32 v[182:183], v[114:115], v[174:175]
	v_pk_mul_f32 v[172:173], v[124:125], v[172:173]
	v_pk_mul_f32 v[174:175], v[122:123], v[174:175]
	v_pk_fma_f32 v[176:177], v[124:125], v[166:167], v[176:177] neg_lo:[0,0,1] neg_hi:[0,0,1]
	v_pk_fma_f32 v[182:183], v[122:123], v[170:171], v[182:183] neg_lo:[0,0,1] neg_hi:[0,0,1]
	v_pk_fma_f32 v[172:173], v[116:117], v[166:167], v[172:173]
	v_pk_fma_f32 v[170:171], v[114:115], v[170:171], v[174:175]
	v_cvt_pk_bf16_f32 v166, v182, v183
	v_cvt_pk_bf16_f32 v167, v176, v177
	s_nop 0
	v_cvt_pk_bf16_f32 v170, v170, v171
	v_cvt_pk_bf16_f32 v171, v172, v173
	global_store_dwordx4 v180, v[164:167], s[82:83]
	global_store_dwordx4 v180, v[168:171], s[82:83] offset:64
	s_nop 0
	s_waitcnt vmcnt(14)
	v_pk_mul_f32 v[166:167], v[138:139], v[202:203] op_sel_hi:[0,1]
	v_pk_mul_f32 v[164:165], v[138:139], v[200:201] op_sel_hi:[0,1]
	v_pk_mul_f32 v[168:169], v[138:139], v[204:205] op_sel_hi:[0,1]
	v_pk_mul_f32 v[170:171], v[138:139], v[206:207] op_sel_hi:[0,1]
	v_pk_mul_f32 v[174:175], v[102:103], v[168:169]
	v_pk_mul_f32 v[176:177], v[104:105], v[166:167]
	v_pk_mul_f32 v[182:183], v[102:103], v[164:165]
	v_pk_mul_f32 v[172:173], v[104:105], v[170:171]
	v_pk_fma_f32 v[164:165], v[110:111], v[164:165], v[174:175] neg_lo:[0,0,1] neg_hi:[0,0,1]
	v_pk_fma_f32 v[170:171], v[112:113], v[170:171], v[176:177]
	v_pk_fma_f32 v[168:169], v[110:111], v[168:169], v[182:183]
	v_pk_fma_f32 v[166:167], v[112:113], v[166:167], v[172:173] neg_lo:[0,0,1] neg_hi:[0,0,1]
	v_cvt_pk_bf16_f32 v164, v164, v165
	s_nop 0
	v_cvt_pk_bf16_f32 v165, v166, v167
	v_cvt_pk_bf16_f32 v168, v168, v169
	v_cvt_pk_bf16_f32 v169, v170, v171
	v_pk_mul_f32 v[154:155], v[138:139], v[210:211] op_sel_hi:[0,1]
	v_pk_mul_f32 v[166:167], v[138:139], v[208:209] op_sel_hi:[0,1]
	v_pk_mul_f32 v[170:171], v[138:139], v[214:215] op_sel_hi:[0,1]
	v_pk_mul_f32 v[172:173], v[138:139], v[212:213] op_sel_hi:[0,1]
	v_pk_mul_f32 v[174:175], v[100:101], v[170:171]
	v_pk_mul_f32 v[176:177], v[98:99], v[172:173]
	v_pk_mul_f32 v[170:171], v[108:109], v[170:171]
	v_pk_mul_f32 v[172:173], v[106:107], v[172:173]
	v_pk_fma_f32 v[174:175], v[108:109], v[154:155], v[174:175] neg_lo:[0,0,1] neg_hi:[0,0,1]
	v_pk_fma_f32 v[176:177], v[106:107], v[166:167], v[176:177] neg_lo:[0,0,1] neg_hi:[0,0,1]
	v_pk_fma_f32 v[154:155], v[100:101], v[154:155], v[170:171]
	v_pk_fma_f32 v[170:171], v[98:99], v[166:167], v[172:173]
	v_cvt_pk_bf16_f32 v166, v176, v177
	v_cvt_pk_bf16_f32 v167, v174, v175
	s_nop 0
	v_cvt_pk_bf16_f32 v170, v170, v171
	v_cvt_pk_bf16_f32 v171, v154, v155
	global_store_dwordx4 v180, v[164:167], s[82:83] offset:2048
	global_store_dwordx4 v180, v[168:171], s[82:83] offset:2112
	s_nop 0
	s_waitcnt vmcnt(12)
	v_pk_mul_f32 v[164:165], v[138:139], v[216:217] op_sel_hi:[0,1]
	v_pk_mul_f32 v[168:169], v[138:139], v[220:221] op_sel_hi:[0,1]
	v_pk_mul_f32 v[154:155], v[138:139], v[218:219] op_sel_hi:[0,1]
	v_pk_mul_f32 v[166:167], v[138:139], v[222:223] op_sel_hi:[0,1]
	v_pk_mul_f32 v[172:173], v[86:87], v[168:169]
	v_pk_mul_f32 v[176:177], v[86:87], v[164:165]
	v_pk_mul_f32 v[170:171], v[88:89], v[166:167]
	v_pk_mul_f32 v[174:175], v[88:89], v[154:155]
	v_pk_fma_f32 v[164:165], v[94:95], v[164:165], v[172:173] neg_lo:[0,0,1] neg_hi:[0,0,1]
	v_pk_fma_f32 v[168:169], v[94:95], v[168:169], v[176:177]
	v_pk_fma_f32 v[154:155], v[96:97], v[154:155], v[170:171] neg_lo:[0,0,1] neg_hi:[0,0,1]
	v_pk_fma_f32 v[166:167], v[96:97], v[166:167], v[174:175]
	v_cvt_pk_bf16_f32 v164, v164, v165
	v_cvt_pk_bf16_f32 v165, v154, v155
	v_cvt_pk_bf16_f32 v168, v168, v169
	v_lshl_add_u64 v[154:155], s[82:83], 0, v[180:181]
	v_cvt_pk_bf16_f32 v169, v166, v167
	v_add_co_u32_e32 v178, vcc, s45, v154
	v_pk_mul_f32 v[166:167], v[138:139], v[226:227] op_sel_hi:[0,1]
	v_pk_mul_f32 v[172:173], v[138:139], v[230:231] op_sel_hi:[0,1]
	v_pk_mul_f32 v[174:175], v[138:139], v[228:229] op_sel_hi:[0,1]
	v_pk_mul_f32 v[170:171], v[138:139], v[224:225] op_sel_hi:[0,1]
	v_pk_mul_f32 v[176:177], v[84:85], v[172:173]
	v_pk_mul_f32 v[180:181], v[82:83], v[174:175]
	v_pk_mul_f32 v[172:173], v[92:93], v[172:173]
	v_pk_mul_f32 v[174:175], v[90:91], v[174:175]
	v_addc_co_u32_e32 v179, vcc, 0, v155, vcc
	v_pk_fma_f32 v[176:177], v[92:93], v[166:167], v[176:177] neg_lo:[0,0,1] neg_hi:[0,0,1]
	v_pk_fma_f32 v[180:181], v[90:91], v[170:171], v[180:181] neg_lo:[0,0,1] neg_hi:[0,0,1]
	v_pk_fma_f32 v[172:173], v[84:85], v[166:167], v[172:173]
	v_pk_fma_f32 v[170:171], v[82:83], v[170:171], v[174:175]
	v_cvt_pk_bf16_f32 v166, v180, v181
	v_cvt_pk_bf16_f32 v167, v176, v177
	s_nop 0
	v_cvt_pk_bf16_f32 v170, v170, v171
	v_cvt_pk_bf16_f32 v171, v172, v173
	global_store_dwordx4 v[178:179], v[164:167], off
	global_store_dwordx4 v[178:179], v[168:171], off offset:64
	s_nop 0
	s_waitcnt vmcnt(10)
	v_pk_mul_f32 v[166:167], v[138:139], v[234:235] op_sel_hi:[0,1]
	v_pk_mul_f32 v[164:165], v[138:139], v[232:233] op_sel_hi:[0,1]
	v_pk_mul_f32 v[168:169], v[138:139], v[236:237] op_sel_hi:[0,1]
	v_pk_mul_f32 v[170:171], v[138:139], v[238:239] op_sel_hi:[0,1]
	v_pk_mul_f32 v[174:175], v[70:71], v[168:169]
	v_pk_mul_f32 v[176:177], v[72:73], v[166:167]
	v_pk_mul_f32 v[180:181], v[70:71], v[164:165]
	v_pk_mul_f32 v[172:173], v[72:73], v[170:171]
	v_pk_fma_f32 v[164:165], v[78:79], v[164:165], v[174:175] neg_lo:[0,0,1] neg_hi:[0,0,1]
	v_pk_fma_f32 v[170:171], v[80:81], v[170:171], v[176:177]
	v_pk_fma_f32 v[168:169], v[78:79], v[168:169], v[180:181]
	v_pk_fma_f32 v[166:167], v[80:81], v[166:167], v[172:173] neg_lo:[0,0,1] neg_hi:[0,0,1]
	v_cvt_pk_bf16_f32 v164, v164, v165
	s_nop 0
	v_cvt_pk_bf16_f32 v165, v166, v167
	v_cvt_pk_bf16_f32 v168, v168, v169
	v_cvt_pk_bf16_f32 v169, v170, v171
	v_add_co_u32_e32 v150, vcc, s55, v148
	v_pk_mul_f32 v[152:153], v[138:139], v[242:243] op_sel_hi:[0,1]
	v_pk_mul_f32 v[166:167], v[138:139], v[240:241] op_sel_hi:[0,1]
	v_pk_mul_f32 v[170:171], v[138:139], v[246:247] op_sel_hi:[0,1]
	v_pk_mul_f32 v[172:173], v[138:139], v[244:245] op_sel_hi:[0,1]
	v_pk_mul_f32 v[174:175], v[68:69], v[170:171]
	v_pk_mul_f32 v[176:177], v[66:67], v[172:173]
	v_pk_mul_f32 v[170:171], v[76:77], v[170:171]
	v_pk_mul_f32 v[172:173], v[74:75], v[172:173]
	v_addc_co_u32_e32 v151, vcc, 0, v149, vcc
	v_pk_fma_f32 v[174:175], v[76:77], v[152:153], v[174:175] neg_lo:[0,0,1] neg_hi:[0,0,1]
	v_pk_fma_f32 v[176:177], v[74:75], v[166:167], v[176:177] neg_lo:[0,0,1] neg_hi:[0,0,1]
	v_pk_fma_f32 v[152:153], v[68:69], v[152:153], v[170:171]
	v_pk_fma_f32 v[170:171], v[66:67], v[166:167], v[172:173]
	v_cvt_pk_bf16_f32 v166, v176, v177
	v_cvt_pk_bf16_f32 v167, v174, v175
	s_nop 0
	v_cvt_pk_bf16_f32 v170, v170, v171
	v_cvt_pk_bf16_f32 v171, v152, v153
	global_store_dwordx4 v[178:179], v[164:167], off offset:2048
	global_store_dwordx4 v[178:179], v[168:171], off offset:2112
	v_add_co_u32_e32 v152, vcc, s54, v148
	s_nop 0
	v_addc_co_u32_e32 v153, vcc, 0, v149, vcc
	v_add_co_u32_e32 v178, vcc, s52, v148
	s_waitcnt vmcnt(8)
	s_barrier
	ds_read_b128 v[184:187], v253
	ds_read_b128 v[188:191], v253 offset:1024
	ds_read_b128 v[192:195], v253 offset:2048
	ds_read_b128 v[196:199], v253 offset:3072
	ds_read_b128 v[200:203], v253 offset:4096
	ds_read_b128 v[204:207], v253 offset:5120
	ds_read_b128 v[208:211], v253 offset:6144
	ds_read_b128 v[212:215], v253 offset:7168
	ds_read_b128 v[216:219], v253 offset:8192
	ds_read_b128 v[220:223], v253 offset:9216
	ds_read_b128 v[224:227], v253 offset:10240
	ds_read_b128 v[228:231], v253 offset:11264
	ds_read_b128 v[232:235], v253 offset:12288
	ds_read_b128 v[236:239], v253 offset:13312
	ds_read_b128 v[240:243], v253 offset:14336
	ds_read_b128 v[244:247], v253 offset:15360
	s_waitcnt lgkmcnt(12)
	v_pk_mul_f32 v[166:167], v[138:139], v[186:187] op_sel_hi:[0,1]
	v_addc_co_u32_e32 v179, vcc, 0, v149, vcc
	v_pk_mul_f32 v[170:171], v[138:139], v[190:191] op_sel_hi:[0,1]
	v_pk_mul_f32 v[168:169], v[138:139], v[188:189] op_sel_hi:[0,1]
	v_pk_mul_f32 v[164:165], v[138:139], v[184:185] op_sel_hi:[0,1]
	v_pk_mul_f32 v[172:173], v[56:57], v[170:171]
	v_pk_mul_f32 v[174:175], v[54:55], v[168:169]
	v_pk_mul_f32 v[168:169], v[62:63], v[168:169]
	v_add_co_u32_e32 v180, vcc, s53, v148
	v_pk_mul_f32 v[170:171], v[64:65], v[170:171]
	v_pk_fma_f32 v[172:173], v[64:65], v[166:167], v[172:173] neg_lo:[0,0,1] neg_hi:[0,0,1]
	v_pk_fma_f32 v[174:175], v[62:63], v[164:165], v[174:175] neg_lo:[0,0,1] neg_hi:[0,0,1]
	v_pk_fma_f32 v[168:169], v[54:55], v[164:165], v[168:169]
	v_addc_co_u32_e32 v181, vcc, 0, v149, vcc
	v_pk_fma_f32 v[166:167], v[56:57], v[166:167], v[170:171]
	v_cvt_pk_bf16_f32 v164, v174, v175
	v_cvt_pk_bf16_f32 v165, v172, v173
	v_cvt_pk_bf16_f32 v168, v168, v169
	v_add_co_u32_e32 v182, vcc, s38, v154
	v_cvt_pk_bf16_f32 v169, v166, v167
	v_addc_co_u32_e32 v183, vcc, 0, v155, vcc
	v_add_co_u32_e32 v148, vcc, s46, v154
	v_pk_mul_f32 v[166:167], v[138:139], v[192:193] op_sel_hi:[0,1]
	v_addc_co_u32_e32 v149, vcc, 0, v155, vcc
	v_pk_mul_f32 v[154:155], v[138:139], v[194:195] op_sel_hi:[0,1]
	v_pk_mul_f32 v[170:171], v[138:139], v[198:199] op_sel_hi:[0,1]
	v_pk_mul_f32 v[172:173], v[138:139], v[196:197] op_sel_hi:[0,1]
	v_pk_mul_f32 v[174:175], v[52:53], v[170:171]
	v_pk_mul_f32 v[176:177], v[50:51], v[172:173]
	v_pk_mul_f32 v[170:171], v[60:61], v[170:171]
	v_pk_mul_f32 v[172:173], v[58:59], v[172:173]
	v_pk_fma_f32 v[174:175], v[60:61], v[154:155], v[174:175] neg_lo:[0,0,1] neg_hi:[0,0,1]
	v_pk_fma_f32 v[176:177], v[58:59], v[166:167], v[176:177] neg_lo:[0,0,1] neg_hi:[0,0,1]
	v_pk_fma_f32 v[154:155], v[52:53], v[154:155], v[170:171]
	v_pk_fma_f32 v[170:171], v[50:51], v[166:167], v[172:173]
	v_cvt_pk_bf16_f32 v166, v176, v177
	v_cvt_pk_bf16_f32 v167, v174, v175
	s_nop 0
	v_cvt_pk_bf16_f32 v170, v170, v171
	v_cvt_pk_bf16_f32 v171, v154, v155
	global_store_dwordx4 v[148:149], v[164:167], off offset:-4096
	global_store_dwordx4 v[182:183], v[168:171], off offset:64
	s_nop 0
	s_waitcnt lgkmcnt(8)
	v_pk_mul_f32 v[164:165], v[138:139], v[200:201] op_sel_hi:[0,1]
	v_pk_mul_f32 v[168:169], v[138:139], v[204:205] op_sel_hi:[0,1]
	v_pk_mul_f32 v[154:155], v[138:139], v[202:203] op_sel_hi:[0,1]
	v_pk_mul_f32 v[166:167], v[138:139], v[206:207] op_sel_hi:[0,1]
	v_pk_mul_f32 v[172:173], v[38:39], v[168:169]
	v_pk_mul_f32 v[176:177], v[38:39], v[164:165]
	v_pk_mul_f32 v[170:171], v[40:41], v[166:167]
	v_pk_mul_f32 v[174:175], v[40:41], v[154:155]
	v_pk_fma_f32 v[164:165], v[46:47], v[164:165], v[172:173] neg_lo:[0,0,1] neg_hi:[0,0,1]
	v_pk_fma_f32 v[168:169], v[46:47], v[168:169], v[176:177]
	v_pk_fma_f32 v[154:155], v[48:49], v[154:155], v[170:171] neg_lo:[0,0,1] neg_hi:[0,0,1]
	v_pk_fma_f32 v[166:167], v[48:49], v[166:167], v[174:175]
	v_cvt_pk_bf16_f32 v164, v164, v165
	v_cvt_pk_bf16_f32 v165, v154, v155
	v_cvt_pk_bf16_f32 v168, v168, v169
	s_nop 0
	v_cvt_pk_bf16_f32 v169, v166, v167
	v_pk_mul_f32 v[154:155], v[138:139], v[210:211] op_sel_hi:[0,1]
	v_pk_mul_f32 v[166:167], v[138:139], v[208:209] op_sel_hi:[0,1]
	v_pk_mul_f32 v[170:171], v[138:139], v[214:215] op_sel_hi:[0,1]
	v_pk_mul_f32 v[172:173], v[138:139], v[212:213] op_sel_hi:[0,1]
	v_pk_mul_f32 v[174:175], v[36:37], v[170:171]
	v_pk_mul_f32 v[176:177], v[34:35], v[172:173]
	v_pk_mul_f32 v[170:171], v[44:45], v[170:171]
	v_pk_mul_f32 v[172:173], v[42:43], v[172:173]
	v_pk_fma_f32 v[174:175], v[44:45], v[154:155], v[174:175] neg_lo:[0,0,1] neg_hi:[0,0,1]
	v_pk_fma_f32 v[176:177], v[42:43], v[166:167], v[176:177] neg_lo:[0,0,1] neg_hi:[0,0,1]
	v_pk_fma_f32 v[154:155], v[36:37], v[154:155], v[170:171]
	v_pk_fma_f32 v[170:171], v[34:35], v[166:167], v[172:173]
	v_cvt_pk_bf16_f32 v166, v176, v177
	v_cvt_pk_bf16_f32 v167, v174, v175
	s_nop 0
	v_cvt_pk_bf16_f32 v170, v170, v171
	v_cvt_pk_bf16_f32 v171, v154, v155
	global_store_dwordx4 v[182:183], v[164:167], off offset:2048
	global_store_dwordx4 v[182:183], v[168:171], off offset:2112
	s_nop 0
	s_waitcnt lgkmcnt(4)
	v_pk_mul_f32 v[164:165], v[138:139], v[216:217] op_sel_hi:[0,1]
	v_pk_mul_f32 v[168:169], v[138:139], v[220:221] op_sel_hi:[0,1]
	v_pk_mul_f32 v[154:155], v[138:139], v[218:219] op_sel_hi:[0,1]
	v_pk_mul_f32 v[166:167], v[138:139], v[222:223] op_sel_hi:[0,1]
	v_pk_mul_f32 v[172:173], v[22:23], v[168:169]
	v_pk_mul_f32 v[176:177], v[22:23], v[164:165]
	v_pk_mul_f32 v[170:171], v[24:25], v[166:167]
	v_pk_mul_f32 v[174:175], v[24:25], v[154:155]
	v_pk_fma_f32 v[164:165], v[30:31], v[164:165], v[172:173] neg_lo:[0,0,1] neg_hi:[0,0,1]
	v_pk_fma_f32 v[168:169], v[30:31], v[168:169], v[176:177]
	v_pk_fma_f32 v[154:155], v[32:33], v[154:155], v[170:171] neg_lo:[0,0,1] neg_hi:[0,0,1]
	v_pk_fma_f32 v[166:167], v[32:33], v[166:167], v[174:175]
	v_cvt_pk_bf16_f32 v164, v164, v165
	v_cvt_pk_bf16_f32 v165, v154, v155
	v_cvt_pk_bf16_f32 v168, v168, v169
	s_nop 0
	v_cvt_pk_bf16_f32 v169, v166, v167
	v_pk_mul_f32 v[154:155], v[138:139], v[226:227] op_sel_hi:[0,1]
	v_pk_mul_f32 v[166:167], v[138:139], v[224:225] op_sel_hi:[0,1]
	v_pk_mul_f32 v[170:171], v[138:139], v[230:231] op_sel_hi:[0,1]
	v_pk_mul_f32 v[172:173], v[138:139], v[228:229] op_sel_hi:[0,1]
	v_pk_mul_f32 v[174:175], v[20:21], v[170:171]
	v_pk_mul_f32 v[176:177], v[18:19], v[172:173]
	v_pk_mul_f32 v[170:171], v[28:29], v[170:171]
	v_pk_mul_f32 v[172:173], v[26:27], v[172:173]
	v_pk_fma_f32 v[174:175], v[28:29], v[154:155], v[174:175] neg_lo:[0,0,1] neg_hi:[0,0,1]
	v_pk_fma_f32 v[176:177], v[26:27], v[166:167], v[176:177] neg_lo:[0,0,1] neg_hi:[0,0,1]
	v_pk_fma_f32 v[154:155], v[20:21], v[154:155], v[170:171]
	v_pk_fma_f32 v[170:171], v[18:19], v[166:167], v[172:173]
	v_cvt_pk_bf16_f32 v166, v176, v177
	v_cvt_pk_bf16_f32 v167, v174, v175
	s_nop 0
	v_cvt_pk_bf16_f32 v170, v170, v171
	v_cvt_pk_bf16_f32 v171, v154, v155
	global_store_dwordx4 v[148:149], v[164:167], off
	global_store_dwordx4 v[148:149], v[168:171], off offset:64
	s_nop 0
	s_waitcnt lgkmcnt(0)
	v_pk_mul_f32 v[164:165], v[138:139], v[232:233] op_sel_hi:[0,1]
	v_pk_mul_f32 v[168:169], v[138:139], v[236:237] op_sel_hi:[0,1]
	v_pk_mul_f32 v[154:155], v[138:139], v[234:235] op_sel_hi:[0,1]
	v_pk_mul_f32 v[166:167], v[138:139], v[238:239] op_sel_hi:[0,1]
	v_pk_mul_f32 v[172:173], v[6:7], v[168:169]
	v_pk_mul_f32 v[176:177], v[6:7], v[164:165]
	v_pk_mul_f32 v[170:171], v[8:9], v[166:167]
	v_pk_mul_f32 v[174:175], v[8:9], v[154:155]
	v_pk_fma_f32 v[164:165], v[14:15], v[164:165], v[172:173] neg_lo:[0,0,1] neg_hi:[0,0,1]
	v_pk_fma_f32 v[168:169], v[14:15], v[168:169], v[176:177]
	v_pk_fma_f32 v[154:155], v[16:17], v[154:155], v[170:171] neg_lo:[0,0,1] neg_hi:[0,0,1]
	v_pk_fma_f32 v[166:167], v[16:17], v[166:167], v[174:175]
	v_cvt_pk_bf16_f32 v164, v164, v165
	v_cvt_pk_bf16_f32 v165, v154, v155
	v_cvt_pk_bf16_f32 v168, v168, v169
	s_nop 0
	v_cvt_pk_bf16_f32 v169, v166, v167
	s_nop 0
	v_pk_mul_f32 v[154:155], v[138:139], v[242:243] op_sel_hi:[0,1]
	v_pk_mul_f32 v[152:153], v[138:139], v[246:247] op_sel_hi:[0,1]
	v_pk_mul_f32 v[150:151], v[138:139], v[244:245] op_sel_hi:[0,1]
	v_pk_mul_f32 v[166:167], v[138:139], v[240:241] op_sel_hi:[0,1]
	v_pk_mul_f32 v[170:171], v[4:5], v[152:153]
	v_pk_mul_f32 v[172:173], v[2:3], v[150:151]
	v_pk_mul_f32 v[150:151], v[10:11], v[150:151]
	v_pk_mul_f32 v[152:153], v[12:13], v[152:153]
	v_pk_fma_f32 v[170:171], v[12:13], v[154:155], v[170:171] neg_lo:[0,0,1] neg_hi:[0,0,1]
	v_pk_fma_f32 v[172:173], v[10:11], v[166:167], v[172:173] neg_lo:[0,0,1] neg_hi:[0,0,1]
	v_pk_fma_f32 v[150:151], v[2:3], v[166:167], v[150:151]
	v_cvt_pk_bf16_f32 v166, v172, v173
	v_cvt_pk_bf16_f32 v167, v170, v171
	v_pk_fma_f32 v[152:153], v[4:5], v[154:155], v[152:153]
	v_cvt_pk_bf16_f32 v170, v150, v151
	s_nop 0
	v_cvt_pk_bf16_f32 v171, v152, v153
	global_store_dwordx4 v[148:149], v[164:167], off offset:2048
	global_store_dwordx4 v[148:149], v[168:171], off offset:2112
